# speedup vs baseline: 1.0242x; 1.0032x over previous
; #define LAS __attribute__((address_space(3)))
; __device__ __forceinline__ unsigned xb_add(unsigned* p, unsigned v) { return __hip_atomic_fetch_add(p, v, __ATOMIC_RELAXED, __HIP_MEMORY_SCOPE_AGENT); }
; __device__ __forceinline__ unsigned xb_xcc_id() { return (unsigned)__builtin_amdgcn_s_getreg((3 << 11) | 20) & 0xFu; }
; __global__ __launch_bounds__(512, 2) void mk_fwd(Params p, int ph_lo, int ph_hi) {
;     extern __shared__ __attribute__((aligned(16))) unsigned char shm[];
;     LAS unsigned char* lds = (LAS unsigned char*)shm;
;     volatile LAS unsigned* st = (volatile LAS unsigned*)(lds + LDS_STATE);
;     unsigned* bar = (unsigned*)(p.ws + WS_CTL);
;     XcdBarrier xb; xb.bar = bar; xb.x = xb_xcc_id(); xb.st = st;
;     if (threadIdx.x == 0) { st[0] = 0u; st[1] = 0u; st[2] = blockIdx.x; st[3] = xb_add(&bar[XB_XCNT(xb.x)], 1u); }
_Z6mk_fwd6Paramsii:
	s_load_dwordx2 s[46:47], s[0:1], 0xa0
	s_load_dwordx8 s[36:43], s[0:1], 0x80
	s_mov_b32 s84, s2
	s_getreg_b32 s2, hwreg(HW_REG_XCC_ID, 0, 4)
	v_and_b32_e32 v200, 0x3ff, v0
	s_waitcnt lgkmcnt(0)
	v_readfirstlane_b32 s3, v200
	s_nop 3
	s_lshr_b32 s3, s3, 6
	s_cmp_lt_u32 s3, 4
	s_cbranch_scc0 .Lprio_skip
	s_setprio 1
